# nt cache hint on read-once f32 inputs in prep (x, expert tables) and on the final output stores
# speedup vs baseline: 1.0037x; 1.0037x over previous
; DI void cvt_stream(const float* __restrict__ src, u16* __restrict__ dst, size_t n, size_t gtid, size_t gn) {
;   size_t n8 = n / 8;
;   for (size_t i = gtid; i < n8; i += gn) {
;     f32x4 a = *reinterpret_cast<const f32x4*>(src + i * 8);
;     f32x4 b = *reinterpret_cast<const f32x4*>(src + i * 8 + 4);
;     u32x4 r; r[0] = pk_bf16(a[0], a[1]); r[1] = pk_bf16(a[2], a[3]); r[2] = pk_bf16(b[0], b[1]); r[3] = pk_bf16(b[2], b[3]);
;     *reinterpret_cast<u32x4*>(dst + i * 8) = r;
;   }
; }
.Lprep_x_loop:
	v_lshl_add_u64 v[22:23], v[4:5], 0, s[8:9]
	v_lshl_add_u64 v[24:25], v[22:23], 0, s[8:9]
	v_lshl_add_u64 v[26:27], v[24:25], 0, s[8:9]
	global_load_dwordx4 v[28:31], v[4:5], off offset:-16 nt
	global_load_dwordx4 v[32:35], v[4:5], off nt
	global_load_dwordx4 v[36:39], v[22:23], off offset:-16 nt
	global_load_dwordx4 v[40:43], v[22:23], off nt
	global_load_dwordx4 v[44:47], v[24:25], off offset:-16 nt
	global_load_dwordx4 v[48:51], v[24:25], off nt
	global_load_dwordx4 v[52:55], v[26:27], off offset:-16 nt
	global_load_dwordx4 v[56:59], v[26:27], off nt
	v_lshl_add_u64 v[4:5], v[26:27], 0, s[8:9]
	s_waitcnt vmcnt(6)
	v_cvt_pk_bf16_f32 v10, v28, v29
	v_cvt_pk_bf16_f32 v11, v30, v31
	v_cvt_pk_bf16_f32 v12, v32, v33
	v_cvt_pk_bf16_f32 v13, v34, v35
	global_store_dwordx4 v[6:7], v[10:13], off
	v_lshl_add_u64 v[6:7], v[6:7], 0, s[10:11]
	s_nop 0
	s_waitcnt vmcnt(5)
	v_cvt_pk_bf16_f32 v10, v36, v37
	v_cvt_pk_bf16_f32 v11, v38, v39
	v_cvt_pk_bf16_f32 v12, v40, v41
	v_cvt_pk_bf16_f32 v13, v42, v43
	global_store_dwordx4 v[6:7], v[10:13], off
	v_lshl_add_u64 v[6:7], v[6:7], 0, s[10:11]
	s_nop 0
	s_waitcnt vmcnt(4)
	v_cvt_pk_bf16_f32 v10, v44, v45
	v_cvt_pk_bf16_f32 v11, v46, v47
	v_cvt_pk_bf16_f32 v12, v48, v49
	v_cvt_pk_bf16_f32 v13, v50, v51
	global_store_dwordx4 v[6:7], v[10:13], off
	v_lshl_add_u64 v[6:7], v[6:7], 0, s[10:11]
	s_nop 0
	s_waitcnt vmcnt(3)
	v_cvt_pk_bf16_f32 v10, v52, v53
	v_cvt_pk_bf16_f32 v11, v54, v55
	v_cvt_pk_bf16_f32 v12, v56, v57
	v_cvt_pk_bf16_f32 v13, v58, v59
	global_store_dwordx4 v[6:7], v[10:13], off
	v_lshl_add_u64 v[6:7], v[6:7], 0, s[10:11]
	s_nop 0
	s_add_i32 s12, s12, -1
	s_cmp_lg_u32 s12, 0
	s_cbranch_scc1 .Lprep_x_loop

; DI void phase_prep(const Params& p, char* smem) {
;     ...
;   {
;     const int lane = threadIdx.x & 63;
;     const int gw = (int)(gtid >> 6), nw = (int)(gn >> 6);
;     for (int r = gw; r < 2 * 16384; r += nw) {
;       const int tbl = r >> 14, row = r & 16383;
;       const float* src = (tbl ? p.ex_up : p.ex_down) + (size_t)row * 1024 + lane * 16;
;       f32x4 v[4]; float mx = 0.f;
; #pragma unroll
;       for (int c = 0; c < 4; ++c) {
;         v[c] = *reinterpret_cast<const f32x4*>(src + c * 4);
.LBB0_11:
	v_writelane_b32 v255, s16, 5
	s_nop 1
	v_writelane_b32 v255, s17, 6
	s_or_b64 exec, exec, s[0:1]
	v_and_b32_e32 v162, 63, v166
	v_alignbit_b32 v22, v19, v18, 6
	s_mov_b32 s0, 0x8000
	v_cmp_gt_i32_e32 vcc, s0, v22
	v_lshlrev_b32_e32 v164, 4, v162
	v_mbcnt_lo_u32_b32 v97, -1, 0
	s_and_saveexec_b64 s[8:9], vcc
	s_cbranch_execz .LBB0_18
	v_mbcnt_hi_u32_b32 v2, -1, v97
	v_and_b32_e32 v1, 64, v2
	v_add_u32_e32 v3, 64, v1
	v_xor_b32_e32 v1, 32, v2
	v_cmp_lt_i32_e32 vcc, v1, v3
	v_xor_b32_e32 v4, 16, v2
	v_readlane_b32 s0, v255, 5
	v_cndmask_b32_e32 v1, v2, v1, vcc
	v_cmp_lt_i32_e32 vcc, v4, v3
	v_readlane_b32 s1, v255, 6
	v_ashrrev_i32_e32 v23, 31, v22
	v_cndmask_b32_e32 v4, v2, v4, vcc
	v_lshlrev_b32_e32 v32, 2, v4
	v_xor_b32_e32 v4, 8, v2
	v_cmp_lt_i32_e32 vcc, v4, v3
	s_lshr_b64 s[10:11], s[0:1], 6
	s_mov_b64 s[0:1], 0xa500000
	v_cndmask_b32_e32 v4, v2, v4, vcc
	v_lshlrev_b32_e32 v33, 2, v4
	v_xor_b32_e32 v4, 4, v2
	v_cmp_lt_i32_e32 vcc, v4, v3
	v_mov_b32_e32 v25, 0
	v_mov_b32_e32 v165, v25
	v_cndmask_b32_e32 v4, v2, v4, vcc
	v_lshlrev_b32_e32 v34, 2, v4
	v_xor_b32_e32 v4, 2, v2
	v_cmp_lt_i32_e32 vcc, v4, v3
	v_cmp_eq_u32_e64 s[4:5], 0, v162
	v_lshlrev_b32_e32 v1, 2, v1
	v_cndmask_b32_e32 v4, v2, v4, vcc
	v_lshlrev_b32_e32 v35, 2, v4
	v_xor_b32_e32 v4, 1, v2
	v_cmp_lt_i32_e32 vcc, v4, v3
	s_lshl_b32 s3, s10, 10
	s_mov_b64 s[14:15], 0
	v_cndmask_b32_e32 v2, v2, v4, vcc
	v_lshlrev_b32_e32 v36, 2, v2
	v_lshl_add_u64 v[2:3], v[22:23], 2, s[96:97]
	v_lshl_add_u64 v[26:27], v[2:3], 0, s[0:1]
	s_bfe_i64 s[0:1], s[10:11], 0x200000
	s_lshl_b64 s[12:13], s[0:1], 2
	v_lshlrev_b32_e32 v23, 10, v22
	s_movk_i32 s11, 0x4000
	s_waitcnt lgkmcnt(0)
	v_mov_b32_e32 v37, s45
	v_mov_b32_e32 v38, s43
	v_mov_b32_e32 v39, s44
	v_mov_b32_e32 v40, s42
	v_lshlrev_b32_e32 v28, 2, v164
	v_mov_b32_e32 v29, v25
	s_mov_b32 s18, 0x43600000
	s_mov_b32 s19, 0x800000
	s_mov_b32 s20, 0xc2fc0000
	v_mov_b32_e32 v41, 0x5000000
	v_bfrev_b32_e32 v42, 32
	s_movk_i32 s21, 0x7fff
	v_mov_b32_e32 v43, 0x42000000
	v_mov_b32_e32 v44, 0x42800000
	v_not_b32_e32 v45, 63
	v_cmp_gt_u32_e64 s[16:17], s11, v22
	v_and_b32_e32 v66, 0xfffc00, v23
	v_lshlrev_b32_e32 v66, 2, v66
	v_mov_b32_e32 v67, 0
	v_cndmask_b32_e64 v69, v37, v38, s[16:17]
	v_cndmask_b32_e64 v68, v39, v40, s[16:17]
	v_lshl_add_u64 v[68:69], v[68:69], 0, v[66:67]
	v_lshl_add_u64 v[68:69], v[68:69], 0, v[28:29]
	global_load_dwordx4 v[50:53], v[68:69], off nt
	global_load_dwordx4 v[54:57], v[68:69], off offset:16 nt
	global_load_dwordx4 v[58:61], v[68:69], off offset:32 nt
	global_load_dwordx4 v[62:65], v[68:69], off offset:48 nt
	s_waitcnt vmcnt(0)
	s_branch .Lprep_e_enter

; DI void phase_prep(const Params& p, char* smem) {
;     ...
;     for (int r = gw; r < 2 * 16384; r += nw) {
;       const int tbl = r >> 14, row = r & 16383;
;       const float* src = (tbl ? p.ex_up : p.ex_down) + (size_t)row * 1024 + lane * 16;
;       f32x4 v[4]; float mx = 0.f;
; #pragma unroll
;       for (int c = 0; c < 4; ++c) {
;         v[c] = *reinterpret_cast<const f32x4*>(src + c * 4);
; #pragma unroll
;         for (int k = 0; k < 4; ++k) mx = fmaxf(mx, fabsf(v[c][k]));
;       }
; #pragma unroll
;       for (int d = 32; d >= 1; d >>= 1) mx = fmaxf(mx, __shfl_xor(mx, d));
;       float sc = (mx > 0.f) ? exp2f(floorf(log2f(224.f / mx))) : 1.f;
.Lprep_e_enter:
	v_cmp_gt_u32_e64 s[0:1], s11, v22
	v_and_b32_e32 v30, 0xfffc00, v23
	v_mov_b64_e32 v[14:15], v[50:51]
	v_mov_b64_e32 v[16:17], v[52:53]
	v_mov_b64_e32 v[10:11], v[54:55]
	v_mov_b64_e32 v[12:13], v[56:57]
	v_mov_b64_e32 v[6:7], v[58:59]
	v_mov_b64_e32 v[8:9], v[60:61]
	v_mov_b64_e32 v[2:3], v[62:63]
	v_mov_b64_e32 v[4:5], v[64:65]
	v_add_u32_e32 v70, s10, v22
	v_min_i32_e32 v70, s21, v70
	v_lshlrev_b32_e32 v71, 10, v70
	v_cmp_gt_u32_e64 s[16:17], s11, v70
	v_and_b32_e32 v66, 0xfffc00, v71
	v_lshlrev_b32_e32 v66, 2, v66
	v_mov_b32_e32 v67, 0
	v_cndmask_b32_e64 v69, v37, v38, s[16:17]
	v_cndmask_b32_e64 v68, v39, v40, s[16:17]
	v_lshl_add_u64 v[68:69], v[68:69], 0, v[66:67]
	v_lshl_add_u64 v[68:69], v[68:69], 0, v[28:29]
	global_load_dwordx4 v[50:53], v[68:69], off nt
	global_load_dwordx4 v[54:57], v[68:69], off offset:16 nt
	global_load_dwordx4 v[58:61], v[68:69], off offset:32 nt
	global_load_dwordx4 v[62:65], v[68:69], off offset:48 nt
	v_mov_b32_e32 v46, 1.0
	v_max3_f32 v24, |v14|, 0, |v15|
	v_max3_f32 v24, v24, |v16|, |v17|
	v_max3_f32 v24, v24, |v10|, |v11|
	v_max3_f32 v24, v24, |v12|, |v13|
	v_max3_f32 v24, v24, |v6|, |v7|
	v_max3_f32 v24, v24, |v8|, |v9|
	v_max3_f32 v24, v24, |v2|, |v3|
	v_max3_f32 v24, v24, |v4|, |v5|
	ds_bpermute_b32 v31, v1, v24
	s_waitcnt lgkmcnt(0)
	v_max_f32_e32 v31, v31, v31
	v_max_f32_e32 v24, v24, v31
	ds_bpermute_b32 v31, v32, v24
	s_waitcnt lgkmcnt(0)
	v_max_f32_e32 v31, v31, v31
	v_max_f32_e32 v24, v24, v31
	ds_bpermute_b32 v31, v33, v24
	s_waitcnt lgkmcnt(0)
	v_max_f32_e32 v31, v31, v31
	v_max_f32_e32 v24, v24, v31
	ds_bpermute_b32 v31, v34, v24
	s_waitcnt lgkmcnt(0)
	v_max_f32_e32 v31, v31, v31
	v_max_f32_e32 v24, v24, v31
	ds_bpermute_b32 v31, v35, v24
	s_waitcnt lgkmcnt(0)
	v_max_f32_e32 v31, v31, v31
	v_max_f32_e32 v24, v24, v31
	ds_bpermute_b32 v31, v36, v24
	s_waitcnt lgkmcnt(0)
	v_max_f32_e32 v31, v31, v31
	v_max_f32_e32 v24, v24, v31
	v_cmp_lt_f32_e32 vcc, 0, v24
	s_and_saveexec_b64 s[16:17], vcc
	s_cbranch_execz .LBB0_16
	v_div_scale_f32 v31, s[22:23], v24, v24, s18
	v_rcp_f32_e32 v46, v31
	v_div_scale_f32 v47, vcc, s18, v24, s18
	v_fma_f32 v48, -v31, v46, 1.0
	v_fmac_f32_e32 v46, v48, v46
	v_mul_f32_e32 v48, v47, v46
	v_fma_f32 v49, -v31, v48, v47
	v_fmac_f32_e32 v48, v49, v46
	v_fma_f32 v31, -v31, v48, v47
	v_div_fmas_f32 v31, v31, v46, v48
	v_div_fixup_f32 v24, v31, v24, s18
	v_cmp_gt_f32_e32 vcc, s19, v24
	s_nop 1
	v_cndmask_b32_e64 v31, 0, 32, vcc
	v_ldexp_f32 v24, v24, v31
	v_log_f32_e32 v24, v24
	v_cndmask_b32_e32 v31, 0, v43, vcc
	v_sub_f32_e32 v24, v24, v31
	v_floor_f32_e32 v24, v24
	v_cmp_gt_f32_e32 vcc, s20, v24
	s_nop 1
	v_cndmask_b32_e32 v31, 0, v44, vcc
	v_add_f32_e32 v24, v24, v31
	v_exp_f32_e32 v24, v24
	v_cndmask_b32_e32 v31, 0, v45, vcc
	v_ldexp_f32 v46, v24, v31

; DI void phase_peer_ffn(const Params& p) {
;     ...
;     const float* xr = h + (size_t)tok * 1024 + lane * 16;
;     float v[16];
; #pragma unroll
;     for (int c = 0; c < 4; ++c) {
;       f32x4 t = *reinterpret_cast<const f32x4*>(xr + c * 4);
; #pragma unroll
;       for (int k = 0; k < 4; ++k) v[4 * c + k] = ALPHA * t[k] + yacc[4 * c + k];
;     }
;     float s = 0.f;
; #pragma unroll
;     for (int i = 0; i < 16; ++i) s += v[i];
;     const float mean = wave_sum(s) * (1.f / 1024.f);
;     float q = 0.f;
; #pragma unroll
;     for (int i = 0; i < 16; ++i) { float d = v[i] - mean; q += d * d; }
;     const float rstd = rsqrtf(wave_sum(q) * (1.f / 1024.f) + 1e-5f);
;     float* orow = p.out + (size_t)tok * 1024 + lane * 16;
; #pragma unroll
;     for (int c = 0; c < 4; ++c) {
;       f32x4 gg = *reinterpret_cast<const f32x4*>(p.ln_ffn_g + lane * 16 + c * 4);
;       f32x4 bb = *reinterpret_cast<const f32x4*>(p.ln_ffn_b + lane * 16 + c * 4);
;       f32x4 o;
; #pragma unroll
;       for (int k = 0; k < 4; ++k) o[k] = (v[4 * c + k] - mean) * rstd * gg[k] + bb[k];
;       *reinterpret_cast<f32x4*>(orow + c * 4) = o;
;     }
.Lpf_ln:
	v_add_u32_e32 v2, s19, v64
	v_lshl_add_u32 v2, v2, 12, v1
	global_load_dwordx4 v[180:183], v2, s[58:59] sc1
	global_load_dwordx4 v[184:187], v2, s[58:59] offset:16 sc1
	global_load_dwordx4 v[188:191], v2, s[58:59] offset:32 sc1
	global_load_dwordx4 v[192:195], v2, s[58:59] offset:48 sc1
	global_load_dwordx4 v[196:199], v2, s[82:83]
	global_load_dwordx4 v[200:203], v2, s[82:83] offset:16
	global_load_dwordx4 v[204:207], v2, s[82:83] offset:32
	global_load_dwordx4 v[208:211], v2, s[82:83] offset:48
	s_waitcnt vmcnt(8)
	v_pk_fma_f32 v[66:67], v[36:37], s[4:5], v[20:21] op_sel_hi:[1,0,1]
	v_pk_fma_f32 v[68:69], v[38:39], s[4:5], v[22:23] op_sel_hi:[1,0,1]
	v_pk_fma_f32 v[70:71], v[40:41], s[4:5], v[24:25] op_sel_hi:[1,0,1]
	v_pk_fma_f32 v[72:73], v[42:43], s[4:5], v[26:27] op_sel_hi:[1,0,1]
	v_pk_fma_f32 v[74:75], v[44:45], s[4:5], v[28:29] op_sel_hi:[1,0,1]
	v_pk_fma_f32 v[76:77], v[46:47], s[4:5], v[30:31] op_sel_hi:[1,0,1]
	v_pk_fma_f32 v[78:79], v[48:49], s[4:5], v[32:33] op_sel_hi:[1,0,1]
	v_pk_fma_f32 v[80:81], v[50:51], s[4:5], v[34:35] op_sel_hi:[1,0,1]
	v_pk_add_f32 v[82:83], v[66:67], v[68:69]
	v_pk_add_f32 v[84:85], v[70:71], v[72:73]
	v_pk_add_f32 v[86:87], v[74:75], v[76:77]
	v_pk_add_f32 v[88:89], v[78:79], v[80:81]
	v_pk_add_f32 v[82:83], v[82:83], v[84:85]
	v_pk_add_f32 v[86:87], v[86:87], v[88:89]
	s_nop 0
	v_pk_add_f32 v[82:83], v[82:83], v[86:87]
	s_nop 0
	v_add_f32_e32 v82, v82, v83
	s_nop 1
	v_add_f32_dpp v83, v82, v82 quad_perm:[1,0,3,2] row_mask:0xf bank_mask:0xf
	s_nop 1
	v_add_f32_dpp v82, v83, v83 quad_perm:[2,3,0,1] row_mask:0xf bank_mask:0xf
	s_nop 1
	v_add_f32_dpp v83, v82, v82 row_half_mirror row_mask:0xf bank_mask:0xf
	s_nop 1
	v_add_f32_dpp v82, v83, v83 row_mirror row_mask:0xf bank_mask:0xf
	s_nop 1
	v_readlane_b32 s20, v82, 0
	v_readlane_b32 s21, v82, 16
	v_readlane_b32 s22, v82, 32
	v_readlane_b32 s23, v82, 48
	s_nop 1
	v_mov_b32_e32 v83, s20
	v_add_f32_e32 v83, s21, v83
	v_add_f32_e32 v83, s22, v83
	v_add_f32_e32 v83, s23, v83
	v_mul_f32_e32 v84, 0x3a800000, v83
	v_mov_b32_e32 v85, v84
	v_pk_add_f32 v[66:67], v[66:67], v[84:85] neg_lo:[0,1] neg_hi:[0,1]
	v_pk_add_f32 v[68:69], v[68:69], v[84:85] neg_lo:[0,1] neg_hi:[0,1]
	v_pk_add_f32 v[70:71], v[70:71], v[84:85] neg_lo:[0,1] neg_hi:[0,1]
	v_pk_add_f32 v[72:73], v[72:73], v[84:85] neg_lo:[0,1] neg_hi:[0,1]
	v_pk_add_f32 v[74:75], v[74:75], v[84:85] neg_lo:[0,1] neg_hi:[0,1]
	v_pk_add_f32 v[76:77], v[76:77], v[84:85] neg_lo:[0,1] neg_hi:[0,1]
	v_pk_add_f32 v[78:79], v[78:79], v[84:85] neg_lo:[0,1] neg_hi:[0,1]
	v_pk_add_f32 v[80:81], v[80:81], v[84:85] neg_lo:[0,1] neg_hi:[0,1]
	v_pk_mul_f32 v[82:83], v[66:67], v[66:67]
	v_pk_mul_f32 v[86:87], v[68:69], v[68:69]
	v_pk_fma_f32 v[82:83], v[70:71], v[70:71], v[82:83]
	v_pk_fma_f32 v[86:87], v[72:73], v[72:73], v[86:87]
	v_pk_fma_f32 v[82:83], v[74:75], v[74:75], v[82:83]
	v_pk_fma_f32 v[86:87], v[76:77], v[76:77], v[86:87]
	v_pk_fma_f32 v[82:83], v[78:79], v[78:79], v[82:83]
	v_pk_fma_f32 v[86:87], v[80:81], v[80:81], v[86:87]
	v_pk_add_f32 v[82:83], v[82:83], v[86:87]
	s_nop 0
	v_add_f32_e32 v82, v82, v83
	s_nop 1
	v_add_f32_dpp v83, v82, v82 quad_perm:[1,0,3,2] row_mask:0xf bank_mask:0xf
	s_nop 1
	v_add_f32_dpp v82, v83, v83 quad_perm:[2,3,0,1] row_mask:0xf bank_mask:0xf
	s_nop 1
	v_add_f32_dpp v83, v82, v82 row_half_mirror row_mask:0xf bank_mask:0xf
	s_nop 1
	v_add_f32_dpp v82, v83, v83 row_mirror row_mask:0xf bank_mask:0xf
	s_nop 1
	v_readlane_b32 s20, v82, 0
	v_readlane_b32 s21, v82, 16
	v_readlane_b32 s22, v82, 32
	v_readlane_b32 s23, v82, 48
	s_nop 1
	v_mov_b32_e32 v83, s20
	v_add_f32_e32 v83, s21, v83
	v_add_f32_e32 v83, s22, v83
	v_add_f32_e32 v83, s23, v83
	v_fmamk_f32 v83, v83, 0x3a800000, v3
	v_rsq_f32_e32 v83, v83
	s_nop 1
	v_mov_b32_e32 v82, v83
	s_nop 0
	v_pk_mul_f32 v[66:67], v[66:67], v[82:83]
	v_pk_mul_f32 v[68:69], v[68:69], v[82:83]
	v_pk_mul_f32 v[70:71], v[70:71], v[82:83]
	v_pk_mul_f32 v[72:73], v[72:73], v[82:83]
	v_pk_mul_f32 v[74:75], v[74:75], v[82:83]
	v_pk_mul_f32 v[76:77], v[76:77], v[82:83]
	v_pk_mul_f32 v[78:79], v[78:79], v[82:83]
	v_pk_mul_f32 v[80:81], v[80:81], v[82:83]
	v_pk_fma_f32 v[66:67], v[66:67], v[100:101], v[116:117]
	v_pk_fma_f32 v[68:69], v[68:69], v[102:103], v[118:119]
	v_pk_fma_f32 v[70:71], v[70:71], v[104:105], v[120:121]
	v_pk_fma_f32 v[72:73], v[72:73], v[106:107], v[122:123]
	v_pk_fma_f32 v[74:75], v[74:75], v[108:109], v[124:125]
	v_pk_fma_f32 v[76:77], v[76:77], v[110:111], v[126:127]
	v_pk_fma_f32 v[78:79], v[78:79], v[112:113], v[128:129]
	v_pk_fma_f32 v[80:81], v[80:81], v[114:115], v[130:131]
	v_add_u32_e32 v2, s18, v64
	v_lshl_add_u32 v2, v2, 12, v1
	global_store_dwordx4 v2, v[66:69], s[58:59] nt
	global_store_dwordx4 v2, v[70:73], s[58:59] offset:16 nt
	global_store_dwordx4 v2, v[74:77], s[58:59] offset:32 nt
	global_store_dwordx4 v2, v[78:81], s[58:59] offset:48 nt
	s_add_i32 s18, s18, 0x1000
	s_min_u32 s26, s18, 0x7800
	v_add_u32_e32 v2, s26, v64
	v_lshl_add_u32 v2, v2, 12, v1
	global_load_dwordx4 v[20:23], v2, s[58:59] sc1
	global_load_dwordx4 v[24:27], v2, s[58:59] offset:16 sc1
	global_load_dwordx4 v[28:31], v2, s[58:59] offset:32 sc1
	global_load_dwordx4 v[32:35], v2, s[58:59] offset:48 sc1
	global_load_dwordx4 v[36:39], v2, s[82:83]
	global_load_dwordx4 v[40:43], v2, s[82:83] offset:16
	global_load_dwordx4 v[44:47], v2, s[82:83] offset:32
	global_load_dwordx4 v[48:51], v2, s[82:83] offset:48
	s_waitcnt vmcnt(12)
; DI void phase_peer_ffn(const Params& p) {
;     ...
;     const float* xr = h + (size_t)tok * 1024 + lane * 16;
;     float v[16];
; #pragma unroll
;     for (int c = 0; c < 4; ++c) {
;       f32x4 t = *reinterpret_cast<const f32x4*>(xr + c * 4);
; #pragma unroll
;       for (int k = 0; k < 4; ++k) v[4 * c + k] = ALPHA * t[k] + yacc[4 * c + k];
;     }
;     float s = 0.f;
; #pragma unroll
;     for (int i = 0; i < 16; ++i) s += v[i];
;     const float mean = wave_sum(s) * (1.f / 1024.f);
;     float q = 0.f;
; #pragma unroll
;     for (int i = 0; i < 16; ++i) { float d = v[i] - mean; q += d * d; }
;     const float rstd = rsqrtf(wave_sum(q) * (1.f / 1024.f) + 1e-5f);
;     float* orow = p.out + (size_t)tok * 1024 + lane * 16;
; #pragma unroll
;     for (int c = 0; c < 4; ++c) {
;       f32x4 gg = *reinterpret_cast<const f32x4*>(p.ln_ffn_g + lane * 16 + c * 4);
;       f32x4 bb = *reinterpret_cast<const f32x4*>(p.ln_ffn_b + lane * 16 + c * 4);
;       f32x4 o;
; #pragma unroll
;       for (int k = 0; k < 4; ++k) o[k] = (v[4 * c + k] - mean) * rstd * gg[k] + bb[k];
;       *reinterpret_cast<f32x4*>(orow + c * 4) = o;
;     }
	v_pk_fma_f32 v[66:67], v[196:197], s[4:5], v[180:181] op_sel_hi:[1,0,1]
	v_pk_fma_f32 v[68:69], v[198:199], s[4:5], v[182:183] op_sel_hi:[1,0,1]
	v_pk_fma_f32 v[70:71], v[200:201], s[4:5], v[184:185] op_sel_hi:[1,0,1]
	v_pk_fma_f32 v[72:73], v[202:203], s[4:5], v[186:187] op_sel_hi:[1,0,1]
	v_pk_fma_f32 v[74:75], v[204:205], s[4:5], v[188:189] op_sel_hi:[1,0,1]
	v_pk_fma_f32 v[76:77], v[206:207], s[4:5], v[190:191] op_sel_hi:[1,0,1]
	v_pk_fma_f32 v[78:79], v[208:209], s[4:5], v[192:193] op_sel_hi:[1,0,1]
	v_pk_fma_f32 v[80:81], v[210:211], s[4:5], v[194:195] op_sel_hi:[1,0,1]
	v_pk_add_f32 v[82:83], v[66:67], v[68:69]
	v_pk_add_f32 v[84:85], v[70:71], v[72:73]
	v_pk_add_f32 v[86:87], v[74:75], v[76:77]
	v_pk_add_f32 v[88:89], v[78:79], v[80:81]
	v_pk_add_f32 v[82:83], v[82:83], v[84:85]
	v_pk_add_f32 v[86:87], v[86:87], v[88:89]
	s_nop 0
	v_pk_add_f32 v[82:83], v[82:83], v[86:87]
	s_nop 0
	v_add_f32_e32 v82, v82, v83
	s_nop 1
	v_add_f32_dpp v83, v82, v82 quad_perm:[1,0,3,2] row_mask:0xf bank_mask:0xf
	s_nop 1
	v_add_f32_dpp v82, v83, v83 quad_perm:[2,3,0,1] row_mask:0xf bank_mask:0xf
	s_nop 1
	v_add_f32_dpp v83, v82, v82 row_half_mirror row_mask:0xf bank_mask:0xf
	s_nop 1
	v_add_f32_dpp v82, v83, v83 row_mirror row_mask:0xf bank_mask:0xf
	s_nop 1
	v_readlane_b32 s20, v82, 0
	v_readlane_b32 s21, v82, 16
	v_readlane_b32 s22, v82, 32
	v_readlane_b32 s23, v82, 48
	s_nop 1
	v_mov_b32_e32 v83, s20
	v_add_f32_e32 v83, s21, v83
	v_add_f32_e32 v83, s22, v83
	v_add_f32_e32 v83, s23, v83
	v_mul_f32_e32 v84, 0x3a800000, v83
	v_mov_b32_e32 v85, v84
	v_pk_add_f32 v[66:67], v[66:67], v[84:85] neg_lo:[0,1] neg_hi:[0,1]
	v_pk_add_f32 v[68:69], v[68:69], v[84:85] neg_lo:[0,1] neg_hi:[0,1]
	v_pk_add_f32 v[70:71], v[70:71], v[84:85] neg_lo:[0,1] neg_hi:[0,1]
	v_pk_add_f32 v[72:73], v[72:73], v[84:85] neg_lo:[0,1] neg_hi:[0,1]
	v_pk_add_f32 v[74:75], v[74:75], v[84:85] neg_lo:[0,1] neg_hi:[0,1]
	v_pk_add_f32 v[76:77], v[76:77], v[84:85] neg_lo:[0,1] neg_hi:[0,1]
	v_pk_add_f32 v[78:79], v[78:79], v[84:85] neg_lo:[0,1] neg_hi:[0,1]
	v_pk_add_f32 v[80:81], v[80:81], v[84:85] neg_lo:[0,1] neg_hi:[0,1]
	v_pk_mul_f32 v[82:83], v[66:67], v[66:67]
	v_pk_mul_f32 v[86:87], v[68:69], v[68:69]
	v_pk_fma_f32 v[82:83], v[70:71], v[70:71], v[82:83]
	v_pk_fma_f32 v[86:87], v[72:73], v[72:73], v[86:87]
	v_pk_fma_f32 v[82:83], v[74:75], v[74:75], v[82:83]
	v_pk_fma_f32 v[86:87], v[76:77], v[76:77], v[86:87]
	v_pk_fma_f32 v[82:83], v[78:79], v[78:79], v[82:83]
	v_pk_fma_f32 v[86:87], v[80:81], v[80:81], v[86:87]
	v_pk_add_f32 v[82:83], v[82:83], v[86:87]
	s_nop 0
	v_add_f32_e32 v82, v82, v83
	s_nop 1
	v_add_f32_dpp v83, v82, v82 quad_perm:[1,0,3,2] row_mask:0xf bank_mask:0xf
	s_nop 1
	v_add_f32_dpp v82, v83, v83 quad_perm:[2,3,0,1] row_mask:0xf bank_mask:0xf
	s_nop 1
	v_add_f32_dpp v83, v82, v82 row_half_mirror row_mask:0xf bank_mask:0xf
	s_nop 1
	v_add_f32_dpp v82, v83, v83 row_mirror row_mask:0xf bank_mask:0xf
	s_nop 1
	v_readlane_b32 s20, v82, 0
	v_readlane_b32 s21, v82, 16
	v_readlane_b32 s22, v82, 32
	v_readlane_b32 s23, v82, 48
	s_nop 1
	v_mov_b32_e32 v83, s20
	v_add_f32_e32 v83, s21, v83
	v_add_f32_e32 v83, s22, v83
	v_add_f32_e32 v83, s23, v83
	v_fmamk_f32 v83, v83, 0x3a800000, v3
	v_rsq_f32_e32 v83, v83
	s_nop 1
	v_mov_b32_e32 v82, v83
	s_nop 0
	v_pk_mul_f32 v[66:67], v[66:67], v[82:83]
	v_pk_mul_f32 v[68:69], v[68:69], v[82:83]
	v_pk_mul_f32 v[70:71], v[70:71], v[82:83]
	v_pk_mul_f32 v[72:73], v[72:73], v[82:83]
	v_pk_mul_f32 v[74:75], v[74:75], v[82:83]
	v_pk_mul_f32 v[76:77], v[76:77], v[82:83]
	v_pk_mul_f32 v[78:79], v[78:79], v[82:83]
	v_pk_mul_f32 v[80:81], v[80:81], v[82:83]
	v_pk_fma_f32 v[66:67], v[66:67], v[100:101], v[116:117]
	v_pk_fma_f32 v[68:69], v[68:69], v[102:103], v[118:119]
	v_pk_fma_f32 v[70:71], v[70:71], v[104:105], v[120:121]
	v_pk_fma_f32 v[72:73], v[72:73], v[106:107], v[122:123]
	v_pk_fma_f32 v[74:75], v[74:75], v[108:109], v[124:125]
	v_pk_fma_f32 v[76:77], v[76:77], v[110:111], v[126:127]
	v_pk_fma_f32 v[78:79], v[78:79], v[112:113], v[128:129]
	v_pk_fma_f32 v[80:81], v[80:81], v[114:115], v[130:131]
	v_add_u32_e32 v2, s19, v64
	v_lshl_add_u32 v2, v2, 12, v1
	global_store_dwordx4 v2, v[66:69], s[58:59] nt
	global_store_dwordx4 v2, v[70:73], s[58:59] offset:16 nt
	global_store_dwordx4 v2, v[74:77], s[58:59] offset:32 nt
	global_store_dwordx4 v2, v[78:81], s[58:59] offset:48 nt
	s_add_i32 s19, s19, 0x1000
	s_cmpk_lt_u32 s18, 0x8000
	s_cbranch_scc1 .Lpf_ln
